# residual GEMM epilogues batched deeper: 16 residual loads in flight (batch 3 lands in the already-stored accumulators of batch 0); otherwise v32
# speedup vs baseline: 1.0027x; 1.0002x over previous
;     __device__ __forceinline__ void operator()(const f32x4 (&acc)[2][2][4][2], const Unit& u, int wr, int wc, int fr, int fq) const {
;         const int row0 = u.pm * BM + wr * 64 + fr; const int col0 = u.pn * BM + wc * 32 + 4 * fq;
;         const float* base = (u.pm * BM < split_row) ? base0 : base1;
; #pragma unroll
;         for (int ai = 0; ai < 2; ++ai)
; #pragma unroll
;             for (int m = 0; m < 4; ++m) { const size_t off = (size_t)(row0 + ai * HALF + m * 16) * ldc + col0;
; #pragma unroll
;                 for (int bj = 0; bj < 2; ++bj)
; #pragma unroll
;                     for (int n = 0; n < 2; ++n) { const f32x4 bs = *(const f32x4*)(base + off + bj * HALF + n * 16); *(f32x4*)(out + off + bj * HALF + n * 16) = bs + acc[ai][bj][m][n]; }
;                 if (m & 1) asm volatile("" ::: "memory"); }
.LBB0_562:
	v_lshl_add_u32 v152, s34, 8, v142
	v_lshl_or_b32 v154, s35, 8, v144
	v_ashrrev_i32_e32 v153, 31, v152
	v_ashrrev_i32_e32 v155, 31, v154
	v_lshlrev_b64 v[140:141], 11, v[152:153]
	s_cmp_lt_i32 s34, 32
	v_lshl_add_u64 v[140:141], v[140:141], 0, v[154:155]
	s_cselect_b32 s35, s13, s74
	s_cselect_b32 s34, s12, s73
	v_lshlrev_b64 v[140:141], 2, v[140:141]
	s_andn2_b64 vcc, exec, s[4:5]
	s_mov_b64 s[4:5], -1
	v_add_u32_e32 v212, 0x20000, v140
	v_add_u32_e32 v213, 0x40000, v140
	v_add_u32_e32 v214, 0x60000, v140
	v_add_u32_e32 v215, 0x100000, v140
	v_add_u32_e32 v216, 0x120000, v140
	v_add_u32_e32 v217, 0x140000, v140
	v_add_u32_e32 v218, 0x160000, v140
	global_load_dwordx4 v[148:151], v140, s[34:35]
	global_load_dwordx4 v[152:155], v140, s[34:35] offset:64
	global_load_dwordx4 v[156:159], v140, s[34:35] offset:512
	global_load_dwordx4 v[160:163], v140, s[34:35] offset:576
	global_load_dwordx4 v[164:167], v212, s[34:35]
	global_load_dwordx4 v[168:171], v212, s[34:35] offset:64
	global_load_dwordx4 v[172:175], v212, s[34:35] offset:512
	global_load_dwordx4 v[176:179], v212, s[34:35] offset:576
	global_load_dwordx4 v[180:183], v213, s[34:35]
	global_load_dwordx4 v[184:187], v213, s[34:35] offset:64
	global_load_dwordx4 v[188:191], v213, s[34:35] offset:512
	global_load_dwordx4 v[192:195], v213, s[34:35] offset:576
	global_load_dwordx4 v[196:199], v214, s[34:35]
	global_load_dwordx4 v[200:203], v214, s[34:35] offset:64
	global_load_dwordx4 v[204:207], v214, s[34:35] offset:512
	global_load_dwordx4 v[208:211], v214, s[34:35] offset:576
	s_waitcnt vmcnt(8)
	v_pk_add_f32 v[124:125], v[124:125], v[148:149]
	v_pk_add_f32 v[126:127], v[126:127], v[150:151]
	global_store_dwordx4 v140, v[124:127], s[48:49]
	v_pk_add_f32 v[120:121], v[120:121], v[152:153]
	v_pk_add_f32 v[122:123], v[122:123], v[154:155]
	global_store_dwordx4 v140, v[120:123], s[48:49] offset:64
	v_pk_add_f32 v[116:117], v[116:117], v[156:157]
	v_pk_add_f32 v[118:119], v[118:119], v[158:159]
	global_store_dwordx4 v140, v[116:119], s[48:49] offset:512
	v_pk_add_f32 v[104:105], v[104:105], v[160:161]
	v_pk_add_f32 v[106:107], v[106:107], v[162:163]
	global_store_dwordx4 v140, v[104:107], s[48:49] offset:576
	v_pk_add_f32 v[112:113], v[112:113], v[164:165]
	v_pk_add_f32 v[114:115], v[114:115], v[166:167]
	global_store_dwordx4 v212, v[112:115], s[48:49]
	v_pk_add_f32 v[108:109], v[108:109], v[168:169]
	v_pk_add_f32 v[110:111], v[110:111], v[170:171]
	global_store_dwordx4 v212, v[108:111], s[48:49] offset:64
	v_pk_add_f32 v[100:101], v[100:101], v[172:173]
	v_pk_add_f32 v[102:103], v[102:103], v[174:175]
	global_store_dwordx4 v212, v[100:103], s[48:49] offset:512
	v_pk_add_f32 v[88:89], v[88:89], v[176:177]
	v_pk_add_f32 v[90:91], v[90:91], v[178:179]
	global_store_dwordx4 v212, v[88:91], s[48:49] offset:576
	global_load_dwordx4 v[148:151], v215, s[34:35]
	global_load_dwordx4 v[152:155], v215, s[34:35] offset:64
	global_load_dwordx4 v[156:159], v215, s[34:35] offset:512
	global_load_dwordx4 v[160:163], v215, s[34:35] offset:576
	global_load_dwordx4 v[164:167], v216, s[34:35]
	global_load_dwordx4 v[168:171], v216, s[34:35] offset:64
	global_load_dwordx4 v[172:175], v216, s[34:35] offset:512
	global_load_dwordx4 v[176:179], v216, s[34:35] offset:576
	global_load_dwordx4 v[124:127], v217, s[34:35]
	global_load_dwordx4 v[120:123], v217, s[34:35] offset:64
	global_load_dwordx4 v[116:119], v217, s[34:35] offset:512
	global_load_dwordx4 v[104:107], v217, s[34:35] offset:576
	global_load_dwordx4 v[112:115], v218, s[34:35]
	global_load_dwordx4 v[108:111], v218, s[34:35] offset:64
	global_load_dwordx4 v[100:103], v218, s[34:35] offset:512
	global_load_dwordx4 v[88:91], v218, s[34:35] offset:576
	s_waitcnt vmcnt(16)
;     __device__ __forceinline__ void operator()(const f32x4 (&acc)[2][2][4][2], const Unit& u, int wr, int wc, int fr, int fq) const {
;     ...
;             for (int m = 0; m < 4; ++m) { const size_t off = (size_t)(row0 + ai * HALF + m * 16) * ldc + col0;
; #pragma unroll
;                 for (int bj = 0; bj < 2; ++bj)
; #pragma unroll
;                     for (int n = 0; n < 2; ++n) { const f32x4 bs = *(const f32x4*)(base + off + bj * HALF + n * 16); *(f32x4*)(out + off + bj * HALF + n * 16) = bs + acc[ai][bj][m][n]; }
;                 if (m & 1) asm volatile("" ::: "memory"); }
	v_pk_add_f32 v[96:97], v[96:97], v[180:181]
	v_pk_add_f32 v[98:99], v[98:99], v[182:183]
	global_store_dwordx4 v213, v[96:99], s[48:49]
	v_pk_add_f32 v[92:93], v[92:93], v[184:185]
	v_pk_add_f32 v[94:95], v[94:95], v[186:187]
	global_store_dwordx4 v213, v[92:95], s[48:49] offset:64
	v_pk_add_f32 v[84:85], v[84:85], v[188:189]
	v_pk_add_f32 v[86:87], v[86:87], v[190:191]
	global_store_dwordx4 v213, v[84:87], s[48:49] offset:512
	v_pk_add_f32 v[72:73], v[72:73], v[192:193]
	v_pk_add_f32 v[74:75], v[74:75], v[194:195]
	global_store_dwordx4 v213, v[72:75], s[48:49] offset:576
	v_pk_add_f32 v[80:81], v[80:81], v[196:197]
	v_pk_add_f32 v[82:83], v[82:83], v[198:199]
	global_store_dwordx4 v214, v[80:83], s[48:49]
	v_pk_add_f32 v[76:77], v[76:77], v[200:201]
	v_pk_add_f32 v[78:79], v[78:79], v[202:203]
	global_store_dwordx4 v214, v[76:79], s[48:49] offset:64
	v_pk_add_f32 v[68:69], v[68:69], v[204:205]
	v_pk_add_f32 v[70:71], v[70:71], v[206:207]
	global_store_dwordx4 v214, v[68:71], s[48:49] offset:512
	v_pk_add_f32 v[64:65], v[64:65], v[208:209]
	v_pk_add_f32 v[66:67], v[66:67], v[210:211]
	global_store_dwordx4 v214, v[64:67], s[48:49] offset:576
	s_waitcnt vmcnt(8)
	v_pk_add_f32 v[60:61], v[60:61], v[148:149]
	v_pk_add_f32 v[62:63], v[62:63], v[150:151]
	global_store_dwordx4 v215, v[60:63], s[48:49]
	v_pk_add_f32 v[56:57], v[56:57], v[152:153]
	v_pk_add_f32 v[58:59], v[58:59], v[154:155]
	global_store_dwordx4 v215, v[56:59], s[48:49] offset:64
	v_pk_add_f32 v[52:53], v[52:53], v[156:157]
	v_pk_add_f32 v[54:55], v[54:55], v[158:159]
	global_store_dwordx4 v215, v[52:55], s[48:49] offset:512
	v_pk_add_f32 v[40:41], v[40:41], v[160:161]
	v_pk_add_f32 v[42:43], v[42:43], v[162:163]
	global_store_dwordx4 v215, v[40:43], s[48:49] offset:576
	v_pk_add_f32 v[48:49], v[48:49], v[164:165]
	v_pk_add_f32 v[50:51], v[50:51], v[166:167]
	global_store_dwordx4 v216, v[48:51], s[48:49]
	v_pk_add_f32 v[44:45], v[44:45], v[168:169]
	v_pk_add_f32 v[46:47], v[46:47], v[170:171]
	global_store_dwordx4 v216, v[44:47], s[48:49] offset:64
	v_pk_add_f32 v[36:37], v[36:37], v[172:173]
	v_pk_add_f32 v[38:39], v[38:39], v[174:175]
	global_store_dwordx4 v216, v[36:39], s[48:49] offset:512
	v_pk_add_f32 v[24:25], v[24:25], v[176:177]
	v_pk_add_f32 v[26:27], v[26:27], v[178:179]
	global_store_dwordx4 v216, v[24:27], s[48:49] offset:576
	s_waitcnt vmcnt(0)
	v_pk_add_f32 v[32:33], v[32:33], v[124:125]
	v_pk_add_f32 v[34:35], v[34:35], v[126:127]
	global_store_dwordx4 v217, v[32:35], s[48:49]
	v_pk_add_f32 v[28:29], v[28:29], v[120:121]
	v_pk_add_f32 v[30:31], v[30:31], v[122:123]
	global_store_dwordx4 v217, v[28:31], s[48:49] offset:64
	v_pk_add_f32 v[20:21], v[20:21], v[116:117]
	v_pk_add_f32 v[22:23], v[22:23], v[118:119]
	global_store_dwordx4 v217, v[20:23], s[48:49] offset:512
	v_pk_add_f32 v[8:9], v[8:9], v[104:105]
	v_pk_add_f32 v[10:11], v[10:11], v[106:107]
	global_store_dwordx4 v217, v[8:11], s[48:49] offset:576
	v_pk_add_f32 v[16:17], v[16:17], v[112:113]
	v_pk_add_f32 v[18:19], v[18:19], v[114:115]
	global_store_dwordx4 v218, v[16:19], s[48:49]
	v_pk_add_f32 v[12:13], v[12:13], v[108:109]
	v_pk_add_f32 v[14:15], v[14:15], v[110:111]
	global_store_dwordx4 v218, v[12:15], s[48:49] offset:64
	v_pk_add_f32 v[4:5], v[4:5], v[100:101]
	v_pk_add_f32 v[6:7], v[6:7], v[102:103]
	global_store_dwordx4 v218, v[4:7], s[48:49] offset:512
	v_pk_add_f32 v[0:1], v[0:1], v[88:89]
	v_pk_add_f32 v[2:3], v[2:3], v[90:91]
	global_store_dwordx4 v218, v[0:3], s[48:49] offset:576
	s_cbranch_vccnz .LBB0_555
	s_andn2_b64 vcc, exec, s[6:7]
	s_cbranch_vccnz .LBB0_554
	s_barrier
	s_branch .LBB0_554

;     __device__ __forceinline__ void operator()(const f32x4 (&acc)[2][2][4][2], const Unit& u, int wr, int wc, int fr, int fq) const {
;         const int row0 = u.pm * BM + wr * 64 + fr; const int col0 = u.pn * BM + wc * 32 + 4 * fq;
;         const float* base = (u.pm * BM < split_row) ? base0 : base1;
; #pragma unroll
;         for (int ai = 0; ai < 2; ++ai)
; #pragma unroll
;             for (int m = 0; m < 4; ++m) { const size_t off = (size_t)(row0 + ai * HALF + m * 16) * ldc + col0;
; #pragma unroll
;                 for (int bj = 0; bj < 2; ++bj)
; #pragma unroll
;                     for (int n = 0; n < 2; ++n) { const f32x4 bs = *(const f32x4*)(base + off + bj * HALF + n * 16); *(f32x4*)(out + off + bj * HALF + n * 16) = bs + acc[ai][bj][m][n]; }
;                 if (m & 1) asm volatile("" ::: "memory"); }
.LBB0_786:
	v_lshl_add_u32 v140, s0, 8, v142
	v_lshl_or_b32 v136, s90, 8, v145
	v_ashrrev_i32_e32 v141, 31, v140
	v_ashrrev_i32_e32 v137, 31, v136
	v_lshlrev_b32_e32 v208, 13, v140
	v_lshl_add_u32 v208, v136, 2, v208
	v_add_u32_e32 v209, 0x20000, v208
	v_add_u32_e32 v210, 0x40000, v208
	v_add_u32_e32 v211, 0x60000, v208
	v_add_u32_e32 v212, 0x100000, v208
	v_add_u32_e32 v213, 0x120000, v208
	v_add_u32_e32 v214, 0x140000, v208
	v_add_u32_e32 v215, 0x160000, v208
	global_load_dwordx4 v[148:151], v208, s[94:95]
	global_load_dwordx4 v[152:155], v208, s[94:95] offset:64
	global_load_dwordx4 v[156:159], v208, s[94:95] offset:512
	global_load_dwordx4 v[160:163], v208, s[94:95] offset:576
	global_load_dwordx4 v[164:167], v209, s[94:95]
	global_load_dwordx4 v[168:171], v209, s[94:95] offset:64
	global_load_dwordx4 v[172:175], v209, s[94:95] offset:512
	global_load_dwordx4 v[176:179], v209, s[94:95] offset:576
	global_load_dwordx4 v[180:183], v210, s[94:95]
	global_load_dwordx4 v[184:187], v210, s[94:95] offset:64
	global_load_dwordx4 v[188:191], v210, s[94:95] offset:512
	global_load_dwordx4 v[192:195], v210, s[94:95] offset:576
	global_load_dwordx4 v[196:199], v211, s[94:95]
	global_load_dwordx4 v[200:203], v211, s[94:95] offset:64
	global_load_dwordx4 v[204:207], v211, s[94:95] offset:512
	global_load_dwordx4 v[136:139], v211, s[94:95] offset:576
	s_waitcnt vmcnt(8)
	v_pk_add_f32 v[124:125], v[124:125], v[148:149]
	v_pk_add_f32 v[126:127], v[126:127], v[150:151]
	global_store_dwordx4 v208, v[124:127], s[94:95]
	v_pk_add_f32 v[120:121], v[120:121], v[152:153]
	v_pk_add_f32 v[122:123], v[122:123], v[154:155]
	global_store_dwordx4 v208, v[120:123], s[94:95] offset:64
	v_pk_add_f32 v[116:117], v[116:117], v[156:157]
	v_pk_add_f32 v[118:119], v[118:119], v[158:159]
	global_store_dwordx4 v208, v[116:119], s[94:95] offset:512
	v_pk_add_f32 v[112:113], v[112:113], v[160:161]
	v_pk_add_f32 v[114:115], v[114:115], v[162:163]
	global_store_dwordx4 v208, v[112:115], s[94:95] offset:576
	v_pk_add_f32 v[108:109], v[108:109], v[164:165]
	v_pk_add_f32 v[110:111], v[110:111], v[166:167]
	global_store_dwordx4 v209, v[108:111], s[94:95]
	v_pk_add_f32 v[104:105], v[104:105], v[168:169]
	v_pk_add_f32 v[106:107], v[106:107], v[170:171]
	global_store_dwordx4 v209, v[104:107], s[94:95] offset:64
	v_pk_add_f32 v[100:101], v[100:101], v[172:173]
	v_pk_add_f32 v[102:103], v[102:103], v[174:175]
	global_store_dwordx4 v209, v[100:103], s[94:95] offset:512
	v_pk_add_f32 v[96:97], v[96:97], v[176:177]
	v_pk_add_f32 v[98:99], v[98:99], v[178:179]
	global_store_dwordx4 v209, v[96:99], s[94:95] offset:576
	global_load_dwordx4 v[148:151], v212, s[94:95]
	global_load_dwordx4 v[152:155], v212, s[94:95] offset:64
	global_load_dwordx4 v[156:159], v212, s[94:95] offset:512
	global_load_dwordx4 v[160:163], v212, s[94:95] offset:576
	global_load_dwordx4 v[164:167], v213, s[94:95]
	global_load_dwordx4 v[168:171], v213, s[94:95] offset:64
	global_load_dwordx4 v[172:175], v213, s[94:95] offset:512
	global_load_dwordx4 v[176:179], v213, s[94:95] offset:576
	global_load_dwordx4 v[124:127], v214, s[94:95]
	global_load_dwordx4 v[120:123], v214, s[94:95] offset:64
	global_load_dwordx4 v[116:119], v214, s[94:95] offset:512
	global_load_dwordx4 v[112:115], v214, s[94:95] offset:576
	global_load_dwordx4 v[108:111], v215, s[94:95]
	global_load_dwordx4 v[104:107], v215, s[94:95] offset:64
	global_load_dwordx4 v[100:103], v215, s[94:95] offset:512
	global_load_dwordx4 v[96:99], v215, s[94:95] offset:576
	s_waitcnt vmcnt(16)
;     __device__ __forceinline__ void operator()(const f32x4 (&acc)[2][2][4][2], const Unit& u, int wr, int wc, int fr, int fq) const {
;     ...
;             for (int m = 0; m < 4; ++m) { const size_t off = (size_t)(row0 + ai * HALF + m * 16) * ldc + col0;
; #pragma unroll
;                 for (int bj = 0; bj < 2; ++bj)
; #pragma unroll
;                     for (int n = 0; n < 2; ++n) { const f32x4 bs = *(const f32x4*)(base + off + bj * HALF + n * 16); *(f32x4*)(out + off + bj * HALF + n * 16) = bs + acc[ai][bj][m][n]; }
;                 if (m & 1) asm volatile("" ::: "memory"); }
	v_pk_add_f32 v[92:93], v[92:93], v[180:181]
	v_pk_add_f32 v[94:95], v[94:95], v[182:183]
	global_store_dwordx4 v210, v[92:95], s[94:95]
	v_pk_add_f32 v[88:89], v[88:89], v[184:185]
	v_pk_add_f32 v[90:91], v[90:91], v[186:187]
	global_store_dwordx4 v210, v[88:91], s[94:95] offset:64
	v_pk_add_f32 v[84:85], v[84:85], v[188:189]
	v_pk_add_f32 v[86:87], v[86:87], v[190:191]
	global_store_dwordx4 v210, v[84:87], s[94:95] offset:512
	v_pk_add_f32 v[80:81], v[80:81], v[192:193]
	v_pk_add_f32 v[82:83], v[82:83], v[194:195]
	global_store_dwordx4 v210, v[80:83], s[94:95] offset:576
	v_pk_add_f32 v[76:77], v[76:77], v[196:197]
	v_pk_add_f32 v[78:79], v[78:79], v[198:199]
	global_store_dwordx4 v211, v[76:79], s[94:95]
	v_pk_add_f32 v[72:73], v[72:73], v[200:201]
	v_pk_add_f32 v[74:75], v[74:75], v[202:203]
	global_store_dwordx4 v211, v[72:75], s[94:95] offset:64
	v_pk_add_f32 v[68:69], v[68:69], v[204:205]
	v_pk_add_f32 v[70:71], v[70:71], v[206:207]
	global_store_dwordx4 v211, v[68:71], s[94:95] offset:512
	v_pk_add_f32 v[64:65], v[64:65], v[136:137]
	v_pk_add_f32 v[66:67], v[66:67], v[138:139]
	global_store_dwordx4 v211, v[64:67], s[94:95] offset:576
	s_waitcnt vmcnt(8)
	v_pk_add_f32 v[60:61], v[60:61], v[148:149]
	v_pk_add_f32 v[62:63], v[62:63], v[150:151]
	global_store_dwordx4 v212, v[60:63], s[94:95]
	v_pk_add_f32 v[56:57], v[56:57], v[152:153]
	v_pk_add_f32 v[58:59], v[58:59], v[154:155]
	global_store_dwordx4 v212, v[56:59], s[94:95] offset:64
	v_pk_add_f32 v[52:53], v[52:53], v[156:157]
	v_pk_add_f32 v[54:55], v[54:55], v[158:159]
	global_store_dwordx4 v212, v[52:55], s[94:95] offset:512
	v_pk_add_f32 v[48:49], v[48:49], v[160:161]
	v_pk_add_f32 v[50:51], v[50:51], v[162:163]
	global_store_dwordx4 v212, v[48:51], s[94:95] offset:576
	v_pk_add_f32 v[44:45], v[44:45], v[164:165]
	v_pk_add_f32 v[46:47], v[46:47], v[166:167]
	global_store_dwordx4 v213, v[44:47], s[94:95]
	v_pk_add_f32 v[40:41], v[40:41], v[168:169]
	v_pk_add_f32 v[42:43], v[42:43], v[170:171]
	global_store_dwordx4 v213, v[40:43], s[94:95] offset:64
	v_pk_add_f32 v[36:37], v[36:37], v[172:173]
	v_pk_add_f32 v[38:39], v[38:39], v[174:175]
	global_store_dwordx4 v213, v[36:39], s[94:95] offset:512
	v_pk_add_f32 v[32:33], v[32:33], v[176:177]
	v_pk_add_f32 v[34:35], v[34:35], v[178:179]
	global_store_dwordx4 v213, v[32:35], s[94:95] offset:576
	s_waitcnt vmcnt(0)
	v_pk_add_f32 v[28:29], v[28:29], v[124:125]
	v_pk_add_f32 v[30:31], v[30:31], v[126:127]
	global_store_dwordx4 v214, v[28:31], s[94:95]
	v_pk_add_f32 v[24:25], v[24:25], v[120:121]
	v_pk_add_f32 v[26:27], v[26:27], v[122:123]
	global_store_dwordx4 v214, v[24:27], s[94:95] offset:64
	v_pk_add_f32 v[20:21], v[20:21], v[116:117]
	v_pk_add_f32 v[22:23], v[22:23], v[118:119]
	global_store_dwordx4 v214, v[20:23], s[94:95] offset:512
	v_pk_add_f32 v[16:17], v[16:17], v[112:113]
	v_pk_add_f32 v[18:19], v[18:19], v[114:115]
	global_store_dwordx4 v214, v[16:19], s[94:95] offset:576
	v_pk_add_f32 v[12:13], v[12:13], v[108:109]
	v_pk_add_f32 v[14:15], v[14:15], v[110:111]
	global_store_dwordx4 v215, v[12:15], s[94:95]
	v_pk_add_f32 v[8:9], v[8:9], v[104:105]
	v_pk_add_f32 v[10:11], v[10:11], v[106:107]
	global_store_dwordx4 v215, v[8:11], s[94:95] offset:64
	v_pk_add_f32 v[4:5], v[4:5], v[100:101]
	v_pk_add_f32 v[6:7], v[6:7], v[102:103]
	global_store_dwordx4 v215, v[4:7], s[94:95] offset:512
	v_pk_add_f32 v[0:1], v[0:1], v[96:97]
	v_pk_add_f32 v[2:3], v[2:3], v[98:99]
	global_store_dwordx4 v215, v[0:3], s[94:95] offset:576
	s_mov_b64 s[0:1], -1
	s_andn2_b64 vcc, exec, s[36:37]
	s_cbranch_vccnz .LBB0_775
	s_andn2_b64 vcc, exec, s[92:93]
	s_cbranch_vccnz .LBB0_774
	s_barrier
	s_branch .LBB0_774
